# adds: next attention work-item index fetched at the end of the current item (atomic overlaps the output-store acks) instead of a separate round trip at the loop top
# speedup vs baseline: 1.0171x; 1.0171x over previous
; #define LAS __attribute__((address_space(3)))
; __device__ __forceinline__ int opaque_tid() { int t = threadIdx.x; asm volatile("" : "+v"(t)); return t; }
; __device__ __forceinline__ int rel_bucket(int n) {
;     if (n < 16) return n;
;     return 16 + (n >= 19) + (n >= 21) + (n >= 24) + (n >= 27) + (n >= 31) + (n >= 35) + (n >= 40) + (n >= 46) + (n >= 52) + (n >= 59) + (n >= 67) + (n >= 77) + (n >= 87) + (n >= 99) + (n >= 113);
; }
; __device__ __forceinline__ void attention_phase(PPtr p, int layer, LAS unsigned char* L, unsigned* counter, const bool do_store) {
;     const int tid = opaque_tid(), lane = tid & 63, wave = tid >> 6, r = lane & 31, h = lane >> 5;
;     unsigned char* big = p->ws + WS_BIG;
;     LAS float* lut = (LAS float*)(L + AL_LUT);
;     LAS float* cb = (LAS float*)(L + AL_CB);
;     LAS float* scan = (LAS float*)(L + AL_SCAN);
;     volatile LAS unsigned* itemw = (volatile LAS unsigned*)(L + AL_ITEM);
;     const float* rel = p->in[1];
;     for (;;) {
;         __syncthreads();
;         if (tid == 0) itemw[0] = atomicAdd(counter, 1u);
;         __syncthreads();
;         const int idx = (int)itemw[0];
.LBB0_494:
	s_and_b64 vcc, exec, s[6:7]
	s_cbranch_vccz .LBB0_690
	s_load_dwordx4 s[24:27], s[42:43], 0xb0
	s_lshl_b32 s1, s16, 2
	v_mov_b32_e32 v190, v214
	s_load_dwordx2 s[46:47], s[42:43], 0x8
	s_waitcnt lgkmcnt(0)
	s_add_u32 s22, s26, s1
	s_addc_u32 s23, s27, 0
	s_lshl_b32 s66, s16, 6
	s_add_i32 s67, 0, 0x12000
	s_add_u32 s2, s26, 0x1b200000
	v_writelane_b32 v255, s2, 34
	s_addc_u32 s2, s27, 0
	v_writelane_b32 v255, s2, 32
	s_add_u32 s2, s26, 0x1ca00000
	v_writelane_b32 v255, s2, 36
	s_addc_u32 s2, s27, 0
	v_writelane_b32 v255, s2, 41
	s_add_u32 s2, s26, 0x1e200000
	v_writelane_b32 v255, s2, 42
	s_addc_u32 s2, s27, 0
	s_waitcnt vmcnt(0)
	v_lshlrev_b32_e32 v2, 3, v190
	v_writelane_b32 v255, s2, 44
	v_ashrrev_i32_e32 v196, 3, v190
	v_and_b32_e32 v156, 56, v2
	s_movk_i32 s2, 0x48
	v_bfe_u32 v5, v190, 5, 1
	v_mad_u64_u32 v[2:3], s[2:3], v196, s2, v[156:157]
	v_and_b32_e32 v194, 31, v190
	v_lshlrev_b32_e32 v198, 2, v5
	v_lshrrev_b32_e32 v3, 2, v190
	s_add_u32 s2, s26, 0x100000
	v_lshlrev_b32_e32 v0, 2, v190
	v_lshlrev_b32_e32 v195, 3, v5
	v_lshl_add_u32 v197, v2, 1, 0
	v_mul_u32_u24_e32 v2, 0x48, v194
	v_and_b32_e32 v6, 16, v190
	v_and_or_b32 v3, v3, 3, v198
	v_writelane_b32 v255, s2, 49
	s_addc_u32 s2, s27, 0
	v_ashrrev_i32_e32 v191, 6, v190
	v_and_or_b32 v6, v0, 12, v6
	v_add_lshl_u32 v199, v195, v2, 1
	v_mul_u32_u24_e32 v2, 0x48, v3
	v_writelane_b32 v255, s2, 47
	v_add_lshl_u32 v200, v2, v6, 1
	v_lshlrev_b32_e32 v2, 2, v191
	v_readlane_b32 s2, v255, 12
	v_lshlrev_b32_e32 v204, 4, v5
	v_cmp_lt_u32_e32 vcc, 18, v190
	v_add_u32_e32 v202, s2, v2
	v_cmp_lt_i32_e64 s[2:3], 0, v191
	v_and_b32_e32 v4, 63, v190
	v_cmp_eq_u32_e64 s[10:11], 0, v4
	v_writelane_b32 v255, s2, 37
	v_cmp_gt_u32_e64 s[12:13], 32, v4
	v_lshlrev_b32_e32 v192, 5, v191
	v_writelane_b32 v255, s3, 38
	s_add_u32 s2, s26, 0xea00000
	v_writelane_b32 v255, s2, 45
	s_addc_u32 s2, s27, 0
	s_add_u32 s77, s26, 0x18200000
	v_writelane_b32 v255, s2, 30
	s_addc_u32 s2, s27, 0
	v_writelane_b32 v255, s2, 39
	s_movk_i32 s2, 0x90
	v_mad_u32_u24 v206, v194, s2, v204
	v_readlane_b32 s2, v255, 13
	s_add_u32 s38, s26, 0x19a00000
	s_addc_u32 s81, s27, 0
	v_add_u32_e32 v209, s2, v2
	v_cndmask_b32_e64 v2, 16, 17, vcc
	v_cmp_lt_u32_e32 vcc, 20, v190
	s_movk_i32 s2, 0x42
	s_add_u32 s82, s26, 0xd200000
	v_cndmask_b32_e64 v4, 0, 1, vcc
	v_cmp_lt_u32_e32 vcc, 23, v190
	s_addc_u32 s83, s27, 0
	s_add_u32 s84, s26, 0x15200000
	v_addc_co_u32_e32 v2, vcc, v2, v4, vcc
	v_cmp_lt_u32_e32 vcc, 26, v190
	s_addc_u32 s85, s27, 0
	s_add_u32 s86, s26, 0x16a00000
	v_cndmask_b32_e64 v4, 0, 1, vcc
	v_cmp_lt_u32_e32 vcc, 30, v190
	s_addc_u32 s87, s27, 0
	s_lshl_b64 s[48:49], s[16:17], 10
	v_addc_co_u32_e32 v2, vcc, v2, v4, vcc
	v_cmp_lt_u32_e32 vcc, 34, v190
	s_add_u32 s50, s42, s1
	s_addc_u32 s51, s43, 0
	v_cndmask_b32_e64 v4, 0, 1, vcc
	v_cmp_lt_u32_e32 vcc, 39, v190
	s_add_u32 s90, s26, 0x11200000
	s_addc_u32 s91, s27, 0
	v_addc_co_u32_e32 v2, vcc, v2, v4, vcc
	v_cmp_lt_u32_e32 vcc, 45, v190
	v_readlane_b32 s1, v255, 14
	v_mul_u32_u24_e32 v3, 0x88, v3
	v_cndmask_b32_e64 v4, 0, 1, vcc
	v_cmp_lt_u32_e32 vcc, 51, v190
	s_add_u32 s92, s26, 0x13200000
	v_add_u32_e32 v210, s1, v0
	v_addc_co_u32_e32 v2, vcc, v2, v4, vcc
	v_cmp_lt_u32_e32 vcc, 58, v190
	s_movk_i32 s1, 0x88
	v_add_lshl_u32 v3, v3, v6, 1
	v_cndmask_b32_e64 v4, 0, 1, vcc
	v_cmp_lt_u32_e32 vcc, s2, v190
	s_movk_i32 s2, 0x4c
	v_add_u32_e32 v193, s67, v0
	v_addc_co_u32_e32 v2, vcc, v2, v4, vcc
	v_cmp_lt_u32_e32 vcc, s2, v190
	s_movk_i32 s2, 0x56
	v_lshlrev_b32_e32 v7, 4, v190
	v_cndmask_b32_e64 v4, 0, 1, vcc
	v_cmp_lt_u32_e32 vcc, s2, v190
	s_movk_i32 s2, 0x62
	s_addc_u32 s93, s27, 0
	v_addc_co_u32_e32 v2, vcc, v2, v4, vcc
	v_cmp_lt_u32_e32 vcc, s2, v190
	s_movk_i32 s2, 0x70
	v_lshlrev_b32_e32 v211, 9, v196
	v_cndmask_b32_e64 v4, 0, 1, vcc
	v_cmp_lt_u32_e32 vcc, s2, v190
	v_mul_lo_u32 v0, v196, s1
	v_add_u32_e32 v213, 0, v3
	v_addc_co_u32_e32 v2, vcc, v2, v4, vcc
	v_cmp_gt_i32_e32 vcc, 16, v190
	v_add_u32_e32 v216, 0x2200, v3
	v_add_u32_e32 v217, 0x3300, v3
	v_cndmask_b32_e32 v2, v2, v190, vcc
	v_mul_lo_u32 v218, v2, 10
	v_or_b32_e32 v2, v192, v194
	s_lshl_b64 s[52:53], s[16:17], 9
	v_sub_u32_e32 v2, v2, v198
	v_mul_lo_u32 v3, v196, s89
	v_add_lshl_u32 v0, v156, v0, 1
	s_add_u32 s94, s24, 0x3000000
	v_subrev_u32_e32 v220, 59, v2
	v_or_b32_e32 v3, v3, v156
	v_add_u32_e32 v223, 0xffffff25, v2
	v_add_u32_e32 v225, 0xffffff3f, v2
	v_or_b32_e32 v226, v211, v156
	v_add_u32_e32 v2, 0, v7
	v_cmp_eq_u32_e64 s[4:5], 0, v190
	v_cmp_gt_i32_e64 s[6:7], s0, v190
	v_add_u32_e32 v201, 0x1200, v200
	v_or_b32_e32 v203, 0xffffa000, v156
	v_mul_u32_u24_e32 v205, 0x90, v194
	v_or_b32_e32 v207, 0xffff4000, v156
	v_or_b32_e32 v208, 0xfffee000, v156
	v_or_b32_e32 v212, 0xffff8000, v156
	s_addc_u32 s95, s25, 0
	v_add_u32_e32 v219, 0xffffff40, v196
	v_add_u32_e32 v221, 0xffffff80, v196
	v_add_u32_e32 v222, 0xc000, v3
	v_add_u32_e32 v224, 0x12000, v3
	v_add_u32_e32 v227, 0x8000, v226
	v_add_u32_e32 v228, 0x12800, v2
	v_add_u32_e32 v229, 0, v0
	s_and_saveexec_b64 s[14:15], s[4:5]
	s_cbranch_execz .Latt_pf0
	v_mov_b32_e32 v252, 1
	global_atomic_add v252, v1, v252, s[22:23] sc0
.Latt_pf0:
	s_mov_b64 exec, s[14:15]
	s_branch .LBB0_499

; __device__ __forceinline__ void attention_phase(PPtr p, int layer, LAS unsigned char* L, unsigned* counter, const bool do_store) {
;     ...
;     for (;;) {
;         __syncthreads();
;         if (tid == 0) itemw[0] = atomicAdd(counter, 1u);
.LBB0_497:
	s_and_saveexec_b64 s[14:15], s[4:5]
	s_cbranch_execz .Latt_pf1
	v_mov_b32_e32 v252, 1
	global_atomic_add v252, v1, v252, s[22:23] sc0
.Latt_pf1:
	s_mov_b64 exec, s[14:15]
	s_mov_b64 s[14:15], 0

; __device__ __forceinline__ void attention_phase(PPtr p, int layer, LAS unsigned char* L, unsigned* counter, const bool do_store) {
;     ...
;     for (;;) {
;         __syncthreads();
;         if (tid == 0) itemw[0] = atomicAdd(counter, 1u);
;         __syncthreads();
;         const int idx = (int)itemw[0];
.LBB0_499:
	s_waitcnt vmcnt(0)
	s_barrier
	s_and_saveexec_b64 s[14:15], s[4:5]
	s_cbranch_execz .LBB0_503
	v_mov_b32_e32 v0, v252
	v_mov_b32_e32 v2, s69
	ds_write_b32 v2, v0
